# v2
# speedup vs baseline: 1.0053x; 1.0053x over previous
; __device__ __forceinline__ void finishSM(f32x16& p0, f32x16& p1, float alpha, float& l_reg, bf16x8& pa0, bf16x8& pa1, bf16x8& pa2, bf16x8& pa3) {
; #pragma unroll
;   for (int r = 0; r < 16; ++r) p1[r] = __builtin_amdgcn_exp2f(p1[r]);
;   float ps = 0;
; #pragma unroll
;   for (int r = 0; r < 16; ++r) ps += p0[r];
; #pragma unroll
;   for (int r = 0; r < 16; ++r) ps += p1[r];
;   { auto rr = __builtin_amdgcn_permlane32_swap(__float_as_uint(ps), __float_as_uint(ps), false, false);
;     ps = __uint_as_float(rr[0]) + __uint_as_float(rr[1]); }
;   l_reg = l_reg * alpha + ps;
;     ...
;   PK4(p0, 0, pa0); PK4(p0, 8, pa1); PK4(p1, 0, pa2); PK4(p1, 8, pa3);
; __device__ __forceinline__ void qkt(f32x16& p0, f32x16& p1, const char* Ks, const char* Krs, const bf16x8* qr, const char* Qrs, int r32, int hi) {
;   p0 = f32x16{}; p1 = f32x16{};
; #pragma unroll
;   for (int d0 = 0; d0 < 8; ++d0) { const int cb = (d0 * 16 + hi * 8) * 2;
;     const bf16x8 b0 = *reinterpret_cast<const bf16x8*>(Ks + KSWZ(r32, cb));
;     const bf16x8 b1 = *reinterpret_cast<const bf16x8*>(Ks + KSWZ(32 + r32, cb));
;     p0 = __builtin_amdgcn_mfma_f32_32x32x16_bf16(b0, qr[d0], p0, 0, 0, 0);
;     p1 = __builtin_amdgcn_mfma_f32_32x32x16_bf16(b1, qr[d0], p1, 0, 0, 0); }
; #pragma unroll
;   for (int d0 = 0; d0 < 4; ++d0) { const int slot = d0 * 2 + hi;
;     const bf16x8 b0 = *reinterpret_cast<const bf16x8*>(Krs + RSWZ(r32, slot));
;     const bf16x8 b1 = *reinterpret_cast<const bf16x8*>(Krs + RSWZ(32 + r32, slot));
;     const bf16x8 qf = *reinterpret_cast<const bf16x8*>(Qrs + RSWZ(r32, slot));
;     p0 = __builtin_amdgcn_mfma_f32_32x32x16_bf16(b0, qf, p0, 0, 0, 0);
;     p1 = __builtin_amdgcn_mfma_f32_32x32x16_bf16(b1, qf, p1, 0, 0, 0); }
; }
.LBB0_353:
	s_add_u32 s46, s70, 0x20000
	s_addc_u32 s47, s71, 0
	ds_read_b128 v[64:67], v169 offset:49152
	ds_read_b128 v[68:71], v169 offset:57344
	ds_read_b128 v[196:199], v170 offset:49152
	ds_read_b128 v[204:207], v170 offset:57344
	v_exp_f32_e32 v158, v134
	v_add_f32_e32 v134, 0, v213
	s_waitcnt lgkmcnt(3)
	s_add_u32 m0, s98, 0x8000
	v_mfma_f32_32x32x16_bf16 v[80:95], v[64:67], v[124:127], 0
	global_load_lds_dwordx4 v130, s[70:71]
	v_add_f32_e32 v134, v217, v134
	v_add_f32_e32 v134, v218, v134
	v_add_f32_e32 v134, v220, v134
	v_add_f32_e32 v134, v221, v134
	v_add_f32_e32 v134, v223, v134
	v_add_f32_e32 v134, v222, v134
	v_add_f32_e32 v134, v224, v134
	s_waitcnt lgkmcnt(2)
	s_add_u32 m0, s98, 0xa000
	v_mfma_f32_32x32x16_bf16 v[64:79], v[68:71], v[124:127], 0
	global_load_lds_dwordx4 v130, s[46:47]
	v_add_f32_e32 v134, v209, v134
	v_add_f32_e32 v134, v210, v134
	v_add_f32_e32 v134, v211, v134
	v_add_f32_e32 v134, v214, v134
	v_exp_f32_e32 v146, v146
	v_add_f32_e32 v134, v212, v134
	v_exp_f32_e32 v147, v147
	s_waitcnt lgkmcnt(1)
	s_add_u32 m0, s98, 0x10000
	v_mfma_f32_32x32x16_bf16 v[80:95], v[196:199], v[120:123], v[80:95]
	global_load_lds_dwordx4 v132, s[72:73]
	v_add_f32_e32 v134, v215, v134
	v_exp_f32_e32 v144, v144
	v_add_f32_e32 v134, v216, v134
	v_exp_f32_e32 v145, v145
	v_add_f32_e32 v134, v219, v134
	v_or_b32_e32 v203, 0x13000, v184
	v_exp_f32_e32 v150, v140
	s_waitcnt lgkmcnt(0)
	s_add_u32 m0, s98, 0x4000
	v_mfma_f32_32x32x16_bf16 v[64:79], v[204:207], v[120:123], v[64:79]
	global_load_lds_dwordx4 v131, s[70:71]
	ds_read_b128 v[196:199], v171 offset:49152
	ds_read_b128 v[204:207], v171 offset:57344
	v_add_f32_e32 v134, v146, v134
	v_exp_f32_e32 v151, v141
	v_add_f32_e32 v134, v147, v134
	v_exp_f32_e32 v156, v136
	v_add_f32_e32 v134, v144, v134
	v_exp_f32_e32 v157, v137
	s_waitcnt lgkmcnt(1)
	s_add_u32 m0, s98, 0x6000
	v_mfma_f32_32x32x16_bf16 v[80:95], v[196:199], v[116:119], v[80:95]
	global_load_lds_dwordx4 v131, s[46:47]
	s_add_u32 s70, s70, 0x40000
	s_addc_u32 s71, s71, 0
	s_add_u32 s72, s72, 0x2000
	s_addc_u32 s73, s73, 0
	v_add_f32_e32 v134, v145, v134
	v_add_f32_e32 v134, v150, v134
	v_exp_f32_e32 v159, v135
	v_add_f32_e32 v134, v151, v134
	v_exp_f32_e32 v148, v148
	v_add_f32_e32 v134, v156, v134
	v_exp_f32_e32 v149, v149
	s_waitcnt lgkmcnt(0)
	v_mfma_f32_32x32x16_bf16 v[64:79], v[204:207], v[116:119], v[64:79]
	ds_read_b128 v[196:199], v172 offset:49152
	ds_read_b128 v[204:207], v172 offset:57344
	v_add_f32_e32 v134, v157, v134
	v_add_f32_e32 v134, v158, v134
	v_exp_f32_e32 v208, v143
	v_add_f32_e32 v134, v159, v134
	v_exp_f32_e32 v225, v138
	v_add_f32_e32 v134, v148, v134
	s_waitcnt lgkmcnt(1)
	v_mfma_f32_32x32x16_bf16 v[80:95], v[196:199], v[112:115], v[80:95]
	v_add_f32_e32 v134, v149, v134
	v_cvt_pk_bf16_f32 v136, v221, v223
	v_cvt_pk_bf16_f32 v135, v218, v220
	v_cvt_pk_bf16_f32 v137, v222, v224
	v_cvt_pk_bf16_f32 v138, v209, v210
	v_cvt_pk_bf16_f32 v140, v212, v215
	v_cvt_pk_bf16_f32 v141, v216, v219
	s_waitcnt lgkmcnt(0)
	v_mfma_f32_32x32x16_bf16 v[64:79], v[204:207], v[112:115], v[64:79]
	ds_read_b128 v[196:199], v173 offset:49152
	ds_read_b128 v[204:207], v173 offset:57344
	v_cvt_pk_bf16_f32 v143, v144, v145
	v_cvt_pk_bf16_f32 v144, v150, v151
	v_cvt_pk_bf16_f32 v145, v156, v157
	v_permlane32_swap_b32_e32 v135, v137
	v_permlane32_swap_b32_e32 v138, v140
	s_waitcnt lgkmcnt(1)
	v_mfma_f32_32x32x16_bf16 v[80:95], v[196:199], v[108:111], v[80:95]
	v_permlane32_swap_b32_e32 v143, v145
	s_waitcnt lgkmcnt(0)
	v_mfma_f32_32x32x16_bf16 v[64:79], v[204:207], v[108:111], v[64:79]
	ds_read_b128 v[196:199], v174 offset:49152
	ds_read_b128 v[204:207], v174 offset:57344
	s_waitcnt lgkmcnt(1)
	v_mfma_f32_32x32x16_bf16 v[80:95], v[196:199], v[104:107], v[80:95]
	s_waitcnt lgkmcnt(0)
	v_mfma_f32_32x32x16_bf16 v[64:79], v[204:207], v[104:107], v[64:79]
	ds_read_b128 v[196:199], v175 offset:49152
	ds_read_b128 v[204:207], v175 offset:57344
	s_waitcnt lgkmcnt(1)
	v_mfma_f32_32x32x16_bf16 v[80:95], v[196:199], v[100:103], v[80:95]
	s_waitcnt lgkmcnt(0)
	v_mfma_f32_32x32x16_bf16 v[64:79], v[204:207], v[100:103], v[64:79]
	ds_read_b128 v[196:199], v176 offset:49152
	ds_read_b128 v[204:207], v176 offset:57344
	s_waitcnt lgkmcnt(1)
	v_mfma_f32_32x32x16_bf16 v[80:95], v[196:199], v[96:99], v[80:95]
	s_waitcnt lgkmcnt(0)
	v_mfma_f32_32x32x16_bf16 v[64:79], v[204:207], v[96:99], v[64:79]
	ds_read_b128 v[196:199], v193
	ds_read_b128 v[204:207], v194
	ds_read_b128 v[226:229], v192
	s_waitcnt lgkmcnt(0)
	v_mfma_f32_32x32x16_bf16 v[80:95], v[196:199], v[226:229], v[80:95]
	v_mfma_f32_32x32x16_bf16 v[64:79], v[204:207], v[226:229], v[64:79]
	ds_read_b128 v[196:199], v189
	ds_read_b128 v[204:207], v190
	ds_read_b128 v[226:229], v191
	s_waitcnt lgkmcnt(0)
	v_mfma_f32_32x32x16_bf16 v[80:95], v[196:199], v[226:229], v[80:95]
	v_or_b32_e32 v196, 0x12000, v181
	v_or_b32_e32 v197, 0x13000, v181
	v_add_u32_e32 v198, v155, v181
	ds_read_b128 v[230:233], v198
	v_or_b32_e32 v199, 0x12000, v184
	v_mfma_f32_32x32x16_bf16 v[64:79], v[204:207], v[226:229], v[64:79]
	ds_read_b128 v[204:207], v196
	ds_read_b128 v[226:229], v197
	s_waitcnt lgkmcnt(1)
	v_mfma_f32_32x32x16_bf16 v[80:95], v[204:207], v[230:233], v[80:95]
	v_add_u32_e32 v204, v155, v184
	ds_read_b128 v[234:237], v204
	v_exp_f32_e32 v207, v142
	v_cvt_pk_bf16_f32 v142, v146, v147
	v_cvt_pk_bf16_f32 v146, v158, v159
	v_cvt_pk_bf16_f32 v147, v148, v149
	v_add_f32_e32 v134, v207, v134
	s_waitcnt lgkmcnt(1)
	v_mfma_f32_32x32x16_bf16 v[64:79], v[226:229], v[230:233], v[64:79]
	ds_read_b128 v[226:229], v199
	ds_read_b128 v[230:233], v203
	v_add_f32_e32 v134, v208, v134
	v_add_f32_e32 v134, v225, v134
	v_cvt_pk_bf16_f32 v148, v207, v208
	v_permlane32_swap_b32_e32 v142, v144
	s_waitcnt lgkmcnt(1)
; #define SBAR() __builtin_amdgcn_sched_barrier(0)
; __device__ __forceinline__ void partialSM(f32x16& p0, f32x16& p1, float& m_reg, float& mn, float& alpha) {
;   constexpr float C = ATT_SCALE * 1.4426950408889634f;
;   float pmax = p0[0];
; #pragma unroll
;   for (int r = 1; r < 16; ++r) pmax = fmaxf(pmax, p0[r]);
; #pragma unroll
;   for (int r = 0; r < 16; ++r) pmax = fmaxf(pmax, p1[r]);
;   { auto rr = __builtin_amdgcn_permlane32_swap(__float_as_uint(pmax), __float_as_uint(pmax), false, false);
;     pmax = fmaxf(__uint_as_float(rr[0]), __uint_as_float(rr[1])); }
;   if (__builtin_expect(__all(pmax - m_reg <= ATT_THR / ATT_SCALE), 1)) { mn = m_reg; alpha = 1.f; }
;   else { mn = fmaxf(m_reg, pmax); alpha = __builtin_amdgcn_exp2f((m_reg - mn) * C); m_reg = mn; }
;   const float mnC = -mn * C;
; #pragma unroll
;   for (int r = 0; r < 16; ++r) p0[r] = fmaf(p0[r], C, mnC);
; #pragma unroll
;   for (int r = 0; r < 16; ++r) p1[r] = fmaf(p1[r], C, mnC);
; #pragma unroll
;   for (int r = 0; r < 16; ++r) p0[r] = __builtin_amdgcn_exp2f(p0[r]);
; template <int D0> __device__ __forceinline__ void pv_one(f32x16& od, int vb, bf16x8 pa0, bf16x8 pa1, bf16x8 pa2, bf16x8 pa3) {
;   const s16x4 l0 = tr_read<v_rd_off(D0, 0, 0)>(vb), h0 = tr_read<v_rd_off(D0, 0, 1)>(vb), l1 = tr_read<v_rd_off(D0, 1, 0)>(vb), h1 = tr_read<v_rd_off(D0, 1, 1)>(vb);
;   const s16x4 l2 = tr_read<v_rd_off(D0, 2, 0)>(vb), h2 = tr_read<v_rd_off(D0, 2, 1)>(vb), l3 = tr_read<v_rd_off(D0, 3, 0)>(vb), h3 = tr_read<v_rd_off(D0, 3, 1)>(vb);
;   asm volatile("s_waitcnt lgkmcnt(0)" ::: "memory"); SBAR();
;     ...
;   od = __builtin_amdgcn_mfma_f32_32x32x16_bf16(pa0, PK(l0, h0), od, 0, 0, 0);
;   od = __builtin_amdgcn_mfma_f32_32x32x16_bf16(pa1, PK(l1, h1), od, 0, 0, 0);
;   od = __builtin_amdgcn_mfma_f32_32x32x16_bf16(pa2, PK(l2, h2), od, 0, 0, 0);
;   od = __builtin_amdgcn_mfma_f32_32x32x16_bf16(pa3, PK(l3, h3), od, 0, 0, 0);
;     ...
; }
; __device__ __forceinline__ void pv_d0(f32x16* o, int vb, bf16x8 pa0, bf16x8 pa1, bf16x8 pa2, bf16x8 pa3) {
;   pv_one<0>(o[0], vb, pa0, pa1, pa2, pa3); pv_one<1>(o[1], vb, pa0, pa1, pa2, pa3); pv_one<2>(o[2], vb, pa0, pa1, pa2, pa3); pv_one<3>(o[3], vb, pa0, pa1, pa2, pa3);
	v_mfma_f32_32x32x16_bf16 v[80:95], v[226:229], v[234:237], v[80:95]
	v_exp_f32_e32 v226, v139
	v_cvt_pk_bf16_f32 v139, v211, v214
	s_nop 1
	v_permlane32_swap_b32_e32 v139, v141
	v_add_f32_e32 v205, v226, v134
	v_mov_b32_e32 v206, v205
	v_cvt_pk_bf16_f32 v134, v213, v217
	s_waitcnt lgkmcnt(0)
	v_mfma_f32_32x32x16_bf16 v[64:79], v[230:233], v[234:237], v[64:79]
	v_permlane32_swap_b32_e32 v205, v206
	v_permlane32_swap_b32_e32 v134, v136
	v_cvt_pk_bf16_f32 v149, v225, v226
	v_permlane32_swap_b32_e32 v146, v148
	s_nop 0
	v_permlane32_swap_b32_e32 v147, v149
	ds_read_b64_tr_b16 v[230:231], v163 offset:0
	ds_read_b64_tr_b16 v[232:233], v163 offset:0x800
	ds_read_b64_tr_b16 v[234:235], v163 offset:0x1000
	ds_read_b64_tr_b16 v[236:237], v163 offset:0x1800
	ds_read_b64_tr_b16 v[238:239], v163 offset:0x2000
	ds_read_b64_tr_b16 v[240:241], v163 offset:0x2800
	ds_read_b64_tr_b16 v[242:243], v163 offset:0x3000
	ds_read_b64_tr_b16 v[244:245], v163 offset:0x3800
	s_waitcnt lgkmcnt(0)
	s_nop 0
	v_mfma_f32_32x32x16_bf16 v[48:63], v[134:137], v[230:233], v[48:63]
	ds_read_b64_tr_b16 v[230:231], v163 offset:0x200
	ds_read_b64_tr_b16 v[232:233], v163 offset:0xa00
	v_max_f32_e32 v164, v81, v81
	v_max_f32_e32 v165, v80, v80
	v_max_f32_e32 v164, v165, v164
	v_max3_f32 v164, v164, v82, v83
	v_max3_f32 v164, v164, v84, v85
	v_mfma_f32_32x32x16_bf16 v[48:63], v[138:141], v[234:237], v[48:63]
	ds_read_b64_tr_b16 v[234:235], v163 offset:0x1200
	ds_read_b64_tr_b16 v[236:237], v163 offset:0x1a00
	v_max3_f32 v164, v164, v86, v87
	v_max3_f32 v164, v164, v88, v89
	v_max3_f32 v164, v164, v90, v91
	v_max3_f32 v164, v164, v92, v93
	v_max3_f32 v164, v164, v94, v95
	v_mfma_f32_32x32x16_bf16 v[48:63], v[142:145], v[238:241], v[48:63]
	ds_read_b64_tr_b16 v[238:239], v163 offset:0x2200
	ds_read_b64_tr_b16 v[240:241], v163 offset:0x2a00
	ds_read_b64_tr_b16 v[246:247], v163 offset:0x3200
	ds_read_b64_tr_b16 v[248:249], v163 offset:0x3a00
	v_max3_f32 v164, v164, v64, v65
	v_max3_f32 v164, v164, v66, v67
	v_max3_f32 v164, v164, v68, v69
	v_max3_f32 v164, v164, v70, v71
	v_max3_f32 v164, v164, v72, v73
	s_waitcnt lgkmcnt(0)
	v_mfma_f32_32x32x16_bf16 v[48:63], v[146:149], v[242:245], v[48:63]
	v_max3_f32 v164, v164, v74, v75
	v_max3_f32 v164, v164, v76, v77
	v_max3_f32 v164, v164, v78, v79
	v_mfma_f32_32x32x16_bf16 v[32:47], v[134:137], v[230:233], v[32:47]
	ds_read_b64_tr_b16 v[230:231], v163 offset:0x400
	ds_read_b64_tr_b16 v[232:233], v163 offset:0xc00
	v_mov_b32_e32 v165, v164
	s_nop 1
	v_permlane32_swap_b32_e32 v164, v165
	v_max_f32_e32 v165, v165, v165
	v_max_f32_e32 v164, v164, v164
	v_max_f32_e32 v164, v164, v165
	v_mfma_f32_32x32x16_bf16 v[32:47], v[138:141], v[234:237], v[32:47]
	ds_read_b64_tr_b16 v[234:235], v163 offset:0x1400
	ds_read_b64_tr_b16 v[236:237], v163 offset:0x1c00
	v_max_f32_e32 v166, v195, v195
	v_sub_f32_e32 v165, v164, v195
	v_max_f32_e32 v164, v166, v164
	v_sub_f32_e32 v166, v195, v164
	v_mul_f32_e32 v166, 0x3dd53b94, v166
	v_mfma_f32_32x32x16_bf16 v[32:47], v[142:145], v[238:241], v[32:47]
	ds_read_b64_tr_b16 v[238:239], v163 offset:0x2400
	ds_read_b64_tr_b16 v[240:241], v163 offset:0x2c00
	ds_read_b64_tr_b16 v[242:243], v163 offset:0x3400
	ds_read_b64_tr_b16 v[244:245], v163 offset:0x3c00
	v_exp_f32_e32 v166, v166
	v_cmp_ge_f32_e32 vcc, s69, v165
	s_cmp_eq_u64 vcc, exec
	s_cselect_b64 s[8:9], -1, 0
	v_cndmask_b32_e64 v208, v166, 1.0, s[8:9]
	v_cndmask_b32_e64 v167, v164, v195, s[8:9]
	v_mul_f32_e32 v207, 0xbdd53b94, v167
	s_waitcnt lgkmcnt(0)
	v_mfma_f32_32x32x16_bf16 v[32:47], v[146:149], v[246:249], v[32:47]
	v_fmamk_f32 v80, v80, 0x3dd53b94, v207
	v_fmamk_f32 v81, v81, 0x3dd53b94, v207
	v_fmamk_f32 v82, v82, 0x3dd53b94, v207
	v_fmamk_f32 v83, v83, 0x3dd53b94, v207
	v_fmamk_f32 v84, v84, 0x3dd53b94, v207
	v_fmamk_f32 v85, v85, 0x3dd53b94, v207
	v_mfma_f32_32x32x16_bf16 v[16:31], v[134:137], v[230:233], v[16:31]
	ds_read_b64_tr_b16 v[230:231], v163 offset:0x600
	ds_read_b64_tr_b16 v[232:233], v163 offset:0xe00
	v_fmamk_f32 v86, v86, 0x3dd53b94, v207
	v_fmamk_f32 v87, v87, 0x3dd53b94, v207
	v_fmamk_f32 v88, v88, 0x3dd53b94, v207
	v_fmamk_f32 v89, v89, 0x3dd53b94, v207
	v_fmamk_f32 v90, v90, 0x3dd53b94, v207
	v_fmamk_f32 v91, v91, 0x3dd53b94, v207
	v_mfma_f32_32x32x16_bf16 v[16:31], v[138:141], v[234:237], v[16:31]
	ds_read_b64_tr_b16 v[234:235], v163 offset:0x1600
	ds_read_b64_tr_b16 v[236:237], v163 offset:0x1e00
	v_fmamk_f32 v92, v92, 0x3dd53b94, v207
	v_fmamk_f32 v93, v93, 0x3dd53b94, v207
	v_fmamk_f32 v94, v94, 0x3dd53b94, v207
	v_fmamk_f32 v95, v95, 0x3dd53b94, v207
	v_fmamk_f32 v217, v64, 0x3dd53b94, v207
	v_fmamk_f32 v218, v65, 0x3dd53b94, v207
	v_mfma_f32_32x32x16_bf16 v[16:31], v[142:145], v[238:241], v[16:31]
	ds_read_b64_tr_b16 v[238:239], v163 offset:0x2600
	ds_read_b64_tr_b16 v[240:241], v163 offset:0x2e00
	ds_read_b64_tr_b16 v[246:247], v163 offset:0x3600
	ds_read_b64_tr_b16 v[248:249], v163 offset:0x3e00
	v_fmamk_f32 v219, v66, 0x3dd53b94, v207
	v_fmamk_f32 v220, v67, 0x3dd53b94, v207
	v_fmamk_f32 v221, v68, 0x3dd53b94, v207
	v_fmamk_f32 v210, v69, 0x3dd53b94, v207
	v_fmamk_f32 v211, v70, 0x3dd53b94, v207
	v_fmamk_f32 v212, v71, 0x3dd53b94, v207
	s_waitcnt lgkmcnt(0)
	v_mfma_f32_32x32x16_bf16 v[16:31], v[146:149], v[242:245], v[16:31]
	v_fmamk_f32 v213, v72, 0x3dd53b94, v207
	v_fmamk_f32 v214, v73, 0x3dd53b94, v207
	v_fmamk_f32 v215, v74, 0x3dd53b94, v207
	v_fmamk_f32 v216, v75, 0x3dd53b94, v207
	v_exp_f32_e32 v195, v85
	v_mfma_f32_32x32x16_bf16 v[0:15], v[134:137], v[230:233], v[0:15]
	v_mov_b32_e32 v134, v167
	v_fmamk_f32 v209, v76, 0x3dd53b94, v207
	v_fmamk_f32 v222, v77, 0x3dd53b94, v207
	v_fmamk_f32 v223, v78, 0x3dd53b94, v207
	v_fmac_f32_e32 v207, 0x3dd53b94, v79
	v_exp_f32_e32 v135, v88
	v_mfma_f32_32x32x16_bf16 v[0:15], v[138:141], v[234:237], v[0:15]
	v_exp_f32_e32 v136, v92
	v_exp_f32_e32 v137, v89
	v_exp_f32_e32 v138, v90
	v_exp_f32_e32 v139, v93
	v_mfma_f32_32x32x16_bf16 v[0:15], v[142:145], v[238:241], v[0:15]
	v_exp_f32_e32 v140, v94
	v_exp_f32_e32 v141, v91
	v_exp_f32_e32 v142, v95
	v_exp_f32_e32 v143, v80
	v_exp_f32_e32 v144, v81
	v_mfma_f32_32x32x16_bf16 v[0:15], v[146:149], v[246:249], v[0:15]
	v_exp_f32_e32 v145, v82
	v_exp_f32_e32 v146, v86
	v_exp_f32_e32 v147, v83
	v_exp_f32_e32 v148, v84
	v_exp_f32_e32 v149, v87
	v_cmp_gt_f32_e32 vcc, 1.0, v208
	s_cbranch_vccz .LBB0_357
; __device__ __forceinline__ void qkt(f32x16& p0, f32x16& p1, const char* Ks, const char* Krs, const bf16x8* qr, const char* Qrs, int r32, int hi) {
;   p0 = f32x16{}; p1 = f32x16{};
; #pragma unroll
;   for (int d0 = 0; d0 < 8; ++d0) { const int cb = (d0 * 16 + hi * 8) * 2;
;     const bf16x8 b0 = *reinterpret_cast<const bf16x8*>(Ks + KSWZ(r32, cb));
;     const bf16x8 b1 = *reinterpret_cast<const bf16x8*>(Ks + KSWZ(32 + r32, cb));
;     p0 = __builtin_amdgcn_mfma_f32_32x32x16_bf16(b0, qr[d0], p0, 0, 0, 0);
;     p1 = __builtin_amdgcn_mfma_f32_32x32x16_bf16(b1, qr[d0], p1, 0, 0, 0); }
; #pragma unroll
;   for (int d0 = 0; d0 < 4; ++d0) { const int slot = d0 * 2 + hi;
;     const bf16x8 b0 = *reinterpret_cast<const bf16x8*>(Krs + RSWZ(r32, slot));
;     const bf16x8 b1 = *reinterpret_cast<const bf16x8*>(Krs + RSWZ(32 + r32, slot));
;     const bf16x8 qf = *reinterpret_cast<const bf16x8*>(Qrs + RSWZ(r32, slot));
;     p0 = __builtin_amdgcn_mfma_f32_32x32x16_bf16(b0, qf, p0, 0, 0, 0);
;     p1 = __builtin_amdgcn_mfma_f32_32x32x16_bf16(b1, qf, p1, 0, 0, 0); }
; }
	s_and_saveexec_b64 s[10:11], s[6:7]
	ds_write_b32 v160, v208 offset:128
	s_or_b64 exec, exec, s[10:11]
	s_waitcnt lgkmcnt(0)
	v_add_u32_e32 v246, v253, v128
	ds_read_b128 v[230:233], v246 offset:224
	ds_read_b128 v[234:237], v246 offset:192
	ds_read_b128 v[238:241], v246 offset:160
	ds_read_b128 v[242:245], v246 offset:128
	s_waitcnt lgkmcnt(3)
	v_pk_mul_f32 v[60:61], v[60:61], v[230:231]
	s_waitcnt lgkmcnt(2)
	v_pk_mul_f32 v[56:57], v[56:57], v[234:235]
	s_waitcnt lgkmcnt(1)
	v_pk_mul_f32 v[52:53], v[52:53], v[238:239]
	v_pk_mul_f32 v[62:63], v[62:63], v[232:233]
	v_pk_mul_f32 v[58:59], v[58:59], v[236:237]
	v_pk_mul_f32 v[54:55], v[54:55], v[240:241]
	s_waitcnt lgkmcnt(0)
	v_pk_mul_f32 v[50:51], v[50:51], v[244:245]
	v_pk_mul_f32 v[48:49], v[48:49], v[242:243]
	v_pk_mul_f32 v[44:45], v[44:45], v[230:231]
	v_pk_mul_f32 v[40:41], v[40:41], v[234:235]
	v_pk_mul_f32 v[36:37], v[36:37], v[238:239]
	v_pk_mul_f32 v[46:47], v[46:47], v[232:233]
	v_pk_mul_f32 v[42:43], v[42:43], v[236:237]
	v_pk_mul_f32 v[38:39], v[38:39], v[240:241]
	v_pk_mul_f32 v[34:35], v[34:35], v[244:245]
	v_pk_mul_f32 v[32:33], v[32:33], v[242:243]
	v_pk_mul_f32 v[28:29], v[28:29], v[230:231]
	v_pk_mul_f32 v[24:25], v[24:25], v[234:235]
	v_pk_mul_f32 v[20:21], v[20:21], v[238:239]
	v_pk_mul_f32 v[30:31], v[30:31], v[232:233]
	v_pk_mul_f32 v[26:27], v[26:27], v[236:237]
	v_pk_mul_f32 v[22:23], v[22:23], v[240:241]
	v_pk_mul_f32 v[18:19], v[18:19], v[244:245]
	v_pk_mul_f32 v[16:17], v[16:17], v[242:243]
	v_pk_mul_f32 v[12:13], v[12:13], v[230:231]
	v_pk_mul_f32 v[8:9], v[8:9], v[234:235]
	v_pk_mul_f32 v[4:5], v[4:5], v[238:239]
	v_pk_mul_f32 v[14:15], v[14:15], v[232:233]
	v_pk_mul_f32 v[10:11], v[10:11], v[236:237]
	v_pk_mul_f32 v[6:7], v[6:7], v[240:241]
	v_pk_mul_f32 v[2:3], v[2:3], v[244:245]
	v_pk_mul_f32 v[0:1], v[0:1], v[242:243]
.LBB0_357:
	s_waitcnt vmcnt(0)
	s_waitcnt lgkmcnt(0)
	s_barrier
	s_add_u32 s46, s70, 0x20000
	s_addc_u32 s47, s71, 0
	ds_read_b128 v[64:67], v169 offset:32768
	ds_read_b128 v[68:71], v169 offset:40960
	ds_read_b128 v[224:227], v170 offset:32768
	ds_read_b128 v[228:231], v170 offset:40960
	v_exp_f32_e32 v159, v210
	v_add_f32_e32 v210, 0, v143
	s_waitcnt lgkmcnt(3)
	s_add_u32 m0, s98, 0xc000
	v_mfma_f32_32x32x16_bf16 v[80:95], v[64:67], v[124:127], 0
	global_load_lds_dwordx4 v130, s[70:71]
	v_add_f32_e32 v210, v144, v210
	v_add_f32_e32 v210, v145, v210
	v_add_f32_e32 v210, v147, v210
	v_add_f32_e32 v210, v148, v210
	v_add_f32_e32 v210, v195, v210
	v_add_f32_e32 v210, v146, v210
	v_add_f32_e32 v210, v149, v210
	s_waitcnt lgkmcnt(2)
	s_add_u32 m0, s98, 0xe000
	v_mfma_f32_32x32x16_bf16 v[64:79], v[68:71], v[124:127], 0
	global_load_lds_dwordx4 v130, s[46:47]
	v_add_f32_e32 v210, v135, v210
	v_add_f32_e32 v210, v137, v210
	v_add_f32_e32 v210, v138, v210
	v_add_f32_e32 v210, v141, v210
	v_exp_f32_e32 v150, v217
	v_add_f32_e32 v210, v136, v210
	v_exp_f32_e32 v151, v218
	s_waitcnt lgkmcnt(1)
	s_add_u32 m0, s98, 0x12000
	v_mfma_f32_32x32x16_bf16 v[80:95], v[224:227], v[120:123], v[80:95]
	global_load_lds_dwordx4 v132, s[72:73]
	v_add_f32_e32 v210, v139, v210
	v_exp_f32_e32 v156, v219
	v_add_f32_e32 v210, v140, v210
	v_exp_f32_e32 v157, v220
	v_add_f32_e32 v210, v142, v210
	v_exp_f32_e32 v158, v221
	v_add_f32_e32 v210, v150, v210
	s_waitcnt lgkmcnt(0)
	s_mov_b32 m0, s98
	v_mfma_f32_32x32x16_bf16 v[64:79], v[228:231], v[120:123], v[64:79]
	global_load_lds_dwordx4 v131, s[70:71]
	ds_read_b128 v[224:227], v171 offset:32768
	ds_read_b128 v[228:231], v171 offset:40960
	v_add_f32_e32 v210, v151, v210
	v_exp_f32_e32 v217, v211
	v_add_f32_e32 v210, v156, v210
	v_exp_f32_e32 v218, v212
	v_add_f32_e32 v210, v157, v210
	v_exp_f32_e32 v219, v213
	s_waitcnt lgkmcnt(1)
	s_add_u32 m0, s98, 0x2000
	v_mfma_f32_32x32x16_bf16 v[80:95], v[224:227], v[116:119], v[80:95]
	global_load_lds_dwordx4 v131, s[46:47]
	s_add_u32 s70, s70, 0x40000
	s_addc_u32 s71, s71, 0
	s_add_u32 s72, s72, 0x2000
	s_addc_u32 s73, s73, 0
	v_add_f32_e32 v210, v158, v210
	v_exp_f32_e32 v214, v214
	v_add_f32_e32 v210, v159, v210
	v_exp_f32_e32 v215, v215
	v_add_f32_e32 v210, v217, v210
	v_exp_f32_e32 v216, v216
	v_add_f32_e32 v210, v218, v210
	s_waitcnt lgkmcnt(0)
	v_mfma_f32_32x32x16_bf16 v[64:79], v[228:231], v[116:119], v[64:79]
	ds_read_b128 v[224:227], v172 offset:32768
	ds_read_b128 v[228:231], v172 offset:40960
	v_exp_f32_e32 v209, v209
	v_add_f32_e32 v210, v219, v210
	v_exp_f32_e32 v220, v222
	v_add_f32_e32 v210, v214, v210
	v_exp_f32_e32 v221, v223
	v_add_f32_e32 v210, v215, v210
	s_waitcnt lgkmcnt(1)
	v_mfma_f32_32x32x16_bf16 v[80:95], v[224:227], v[112:115], v[80:95]
	v_exp_f32_e32 v207, v207
	v_add_f32_e32 v210, v216, v210
	v_add_f32_e32 v210, v209, v210
	v_add_f32_e32 v210, v220, v210
	v_add_f32_e32 v210, v221, v210
	v_cvt_pk_bf16_f32 v211, v145, v147
	v_cvt_pk_bf16_f32 v212, v148, v195
	s_waitcnt lgkmcnt(0)
	v_mfma_f32_32x32x16_bf16 v[64:79], v[228:231], v[112:115], v[64:79]
	ds_read_b128 v[224:227], v173 offset:32768
	ds_read_b128 v[228:231], v173 offset:40960
	v_cvt_pk_bf16_f32 v213, v146, v149
	v_cvt_pk_bf16_f32 v145, v138, v141
	v_cvt_pk_bf16_f32 v146, v136, v139
	v_cvt_pk_bf16_f32 v147, v140, v142
	v_cvt_pk_bf16_f32 v136, v150, v151
	v_cvt_pk_bf16_f32 v138, v158, v159
	s_waitcnt lgkmcnt(1)
	v_mfma_f32_32x32x16_bf16 v[80:95], v[224:227], v[108:111], v[80:95]
	v_cvt_pk_bf16_f32 v139, v217, v218
	v_cvt_pk_bf16_f32 v140, v219, v214
	v_cvt_pk_bf16_f32 v141, v215, v216
	v_cvt_pk_bf16_f32 v142, v209, v220
	v_permlane32_swap_b32_e32 v211, v213
	v_permlane32_swap_b32_e32 v145, v147
	s_waitcnt lgkmcnt(0)
; #define SBAR() __builtin_amdgcn_sched_barrier(0)
; __device__ __forceinline__ void partialSM(f32x16& p0, f32x16& p1, float& m_reg, float& mn, float& alpha) {
;   constexpr float C = ATT_SCALE * 1.4426950408889634f;
;   float pmax = p0[0];
; #pragma unroll
;   for (int r = 1; r < 16; ++r) pmax = fmaxf(pmax, p0[r]);
; #pragma unroll
;   for (int r = 0; r < 16; ++r) pmax = fmaxf(pmax, p1[r]);
;   { auto rr = __builtin_amdgcn_permlane32_swap(__float_as_uint(pmax), __float_as_uint(pmax), false, false);
;     pmax = fmaxf(__uint_as_float(rr[0]), __uint_as_float(rr[1])); }
;   if (__builtin_expect(__all(pmax - m_reg <= ATT_THR / ATT_SCALE), 1)) { mn = m_reg; alpha = 1.f; }
;   else { mn = fmaxf(m_reg, pmax); alpha = __builtin_amdgcn_exp2f((m_reg - mn) * C); m_reg = mn; }
;   const float mnC = -mn * C;
; #pragma unroll
;   for (int r = 0; r < 16; ++r) p0[r] = fmaf(p0[r], C, mnC);
; #pragma unroll
;   for (int r = 0; r < 16; ++r) p1[r] = fmaf(p1[r], C, mnC);
; #pragma unroll
;   for (int r = 0; r < 16; ++r) p0[r] = __builtin_amdgcn_exp2f(p0[r]);
; template <int D0> __device__ __forceinline__ void pv_one(f32x16& od, int vb, bf16x8 pa0, bf16x8 pa1, bf16x8 pa2, bf16x8 pa3) {
;   const s16x4 l0 = tr_read<v_rd_off(D0, 0, 0)>(vb), h0 = tr_read<v_rd_off(D0, 0, 1)>(vb), l1 = tr_read<v_rd_off(D0, 1, 0)>(vb), h1 = tr_read<v_rd_off(D0, 1, 1)>(vb);
;   const s16x4 l2 = tr_read<v_rd_off(D0, 2, 0)>(vb), h2 = tr_read<v_rd_off(D0, 2, 1)>(vb), l3 = tr_read<v_rd_off(D0, 3, 0)>(vb), h3 = tr_read<v_rd_off(D0, 3, 1)>(vb);
;   asm volatile("s_waitcnt lgkmcnt(0)" ::: "memory"); SBAR();
;     ...
;   od = __builtin_amdgcn_mfma_f32_32x32x16_bf16(pa0, PK(l0, h0), od, 0, 0, 0);
;   od = __builtin_amdgcn_mfma_f32_32x32x16_bf16(pa1, PK(l1, h1), od, 0, 0, 0);
;   od = __builtin_amdgcn_mfma_f32_32x32x16_bf16(pa2, PK(l2, h2), od, 0, 0, 0);
;   od = __builtin_amdgcn_mfma_f32_32x32x16_bf16(pa3, PK(l3, h3), od, 0, 0, 0);
;     ...
; }
; __device__ __forceinline__ void pv_d0(f32x16* o, int vb, bf16x8 pa0, bf16x8 pa1, bf16x8 pa2, bf16x8 pa3) {
;   pv_one<0>(o[0], vb, pa0, pa1, pa2, pa3); pv_one<1>(o[1], vb, pa0, pa1, pa2, pa3); pv_one<2>(o[2], vb, pa0, pa1, pa2, pa3); pv_one<3>(o[3], vb, pa0, pa1, pa2, pa3);
	v_mfma_f32_32x32x16_bf16 v[64:79], v[228:231], v[108:111], v[64:79]
	ds_read_b128 v[224:227], v174 offset:32768
	ds_read_b128 v[228:231], v174 offset:40960
	v_permlane32_swap_b32_e32 v136, v138
	v_permlane32_swap_b32_e32 v140, v142
	s_waitcnt lgkmcnt(1)
	v_mfma_f32_32x32x16_bf16 v[80:95], v[224:227], v[104:107], v[80:95]
	s_waitcnt lgkmcnt(0)
	v_mfma_f32_32x32x16_bf16 v[64:79], v[228:231], v[104:107], v[64:79]
	ds_read_b128 v[224:227], v175 offset:32768
	ds_read_b128 v[228:231], v175 offset:40960
	s_waitcnt lgkmcnt(1)
	v_mfma_f32_32x32x16_bf16 v[80:95], v[224:227], v[100:103], v[80:95]
	s_waitcnt lgkmcnt(0)
	v_mfma_f32_32x32x16_bf16 v[64:79], v[228:231], v[100:103], v[64:79]
	ds_read_b128 v[224:227], v176 offset:32768
	ds_read_b128 v[228:231], v176 offset:40960
	s_waitcnt lgkmcnt(1)
	v_mfma_f32_32x32x16_bf16 v[80:95], v[224:227], v[96:99], v[80:95]
	s_waitcnt lgkmcnt(0)
	v_mfma_f32_32x32x16_bf16 v[64:79], v[228:231], v[96:99], v[64:79]
	ds_read_b128 v[224:227], v177
	ds_read_b128 v[228:231], v178
	ds_read_b128 v[232:235], v192
	s_waitcnt lgkmcnt(0)
	v_mfma_f32_32x32x16_bf16 v[80:95], v[224:227], v[232:235], v[80:95]
	v_mfma_f32_32x32x16_bf16 v[64:79], v[228:231], v[232:235], v[64:79]
	ds_read_b128 v[224:227], v179
	ds_read_b128 v[228:231], v180
	ds_read_b128 v[232:235], v191
	s_waitcnt lgkmcnt(0)
	v_mfma_f32_32x32x16_bf16 v[80:95], v[224:227], v[232:235], v[80:95]
	v_mfma_f32_32x32x16_bf16 v[64:79], v[228:231], v[232:235], v[64:79]
	ds_read_b128 v[224:227], v182
	ds_read_b128 v[228:231], v183
	ds_read_b128 v[232:235], v198
	s_waitcnt lgkmcnt(0)
	v_mfma_f32_32x32x16_bf16 v[80:95], v[224:227], v[232:235], v[80:95]
	v_mfma_f32_32x32x16_bf16 v[64:79], v[228:231], v[232:235], v[64:79]
	ds_read_b128 v[224:227], v185
	ds_read_b128 v[228:231], v186
	ds_read_b128 v[232:235], v204
	s_waitcnt lgkmcnt(0)
	v_mfma_f32_32x32x16_bf16 v[80:95], v[224:227], v[232:235], v[80:95]
	v_add_f32_e32 v225, v207, v210
	v_mov_b32_e32 v226, v225
	s_nop 1
	v_permlane32_swap_b32_e32 v225, v226
	v_cvt_pk_bf16_f32 v210, v143, v144
	v_cvt_pk_bf16_f32 v144, v135, v137
	v_cvt_pk_bf16_f32 v137, v156, v157
	v_mfma_f32_32x32x16_bf16 v[64:79], v[228:231], v[232:235], v[64:79]
	v_cvt_pk_bf16_f32 v143, v221, v207
	v_permlane32_swap_b32_e32 v210, v212
	v_permlane32_swap_b32_e32 v144, v146
	v_permlane32_swap_b32_e32 v137, v139
	v_permlane32_swap_b32_e32 v141, v143
	ds_read_b64_tr_b16 v[240:241], v162 offset:0
	ds_read_b64_tr_b16 v[242:243], v162 offset:0x800
	ds_read_b64_tr_b16 v[244:245], v162 offset:0x1000
	ds_read_b64_tr_b16 v[246:247], v162 offset:0x1800
	ds_read_b64_tr_b16 v[248:249], v162 offset:0x2000
	ds_read_b64_tr_b16 v[250:251], v162 offset:0x2800
	ds_read_b64_tr_b16 v[148:149], v162 offset:0x3000
	ds_read_b64_tr_b16 v[150:151], v162 offset:0x3800
	s_waitcnt lgkmcnt(0)
	s_nop 0
	v_mfma_f32_32x32x16_bf16 v[48:63], v[210:213], v[240:243], v[48:63]
	ds_read_b64_tr_b16 v[240:241], v162 offset:0x200
	ds_read_b64_tr_b16 v[242:243], v162 offset:0xa00
	v_max_f32_e32 v164, v81, v81
	v_max_f32_e32 v165, v80, v80
	v_max_f32_e32 v164, v165, v164
	v_max3_f32 v164, v164, v82, v83
	v_max3_f32 v164, v164, v84, v85
	v_mfma_f32_32x32x16_bf16 v[48:63], v[144:147], v[244:247], v[48:63]
	ds_read_b64_tr_b16 v[244:245], v162 offset:0x1200
	ds_read_b64_tr_b16 v[246:247], v162 offset:0x1a00
	v_max3_f32 v164, v164, v86, v87
	v_max3_f32 v164, v164, v88, v89
	v_max3_f32 v164, v164, v90, v91
	v_max3_f32 v164, v164, v92, v93
	v_max3_f32 v164, v164, v94, v95
	v_mfma_f32_32x32x16_bf16 v[48:63], v[136:139], v[248:251], v[48:63]
	ds_read_b64_tr_b16 v[248:249], v162 offset:0x2200
	ds_read_b64_tr_b16 v[250:251], v162 offset:0x2a00
	ds_read_b64_tr_b16 v[156:157], v162 offset:0x3200
	ds_read_b64_tr_b16 v[158:159], v162 offset:0x3a00
	v_max3_f32 v164, v164, v64, v65
	v_max3_f32 v164, v164, v66, v67
	v_max3_f32 v164, v164, v68, v69
	v_max3_f32 v164, v164, v70, v71
	v_max3_f32 v164, v164, v72, v73
	s_waitcnt lgkmcnt(0)
	v_mfma_f32_32x32x16_bf16 v[48:63], v[140:143], v[148:151], v[48:63]
	v_max3_f32 v164, v164, v74, v75
	v_max3_f32 v164, v164, v76, v77
	v_max3_f32 v164, v164, v78, v79
	v_mfma_f32_32x32x16_bf16 v[32:47], v[210:213], v[240:243], v[32:47]
	ds_read_b64_tr_b16 v[148:149], v162 offset:0x400
	ds_read_b64_tr_b16 v[150:151], v162 offset:0xc00
	ds_read_b64_tr_b16 v[240:241], v162 offset:0x1400
	ds_read_b64_tr_b16 v[242:243], v162 offset:0x1c00
	v_mov_b32_e32 v165, v164
	s_nop 1
	v_permlane32_swap_b32_e32 v164, v165
	v_max_f32_e32 v165, v165, v165
	v_max_f32_e32 v164, v164, v164
	v_max_f32_e32 v164, v164, v165
	v_mfma_f32_32x32x16_bf16 v[32:47], v[144:147], v[244:247], v[32:47]
	ds_read_b64_tr_b16 v[244:245], v162 offset:0x2400
	ds_read_b64_tr_b16 v[246:247], v162 offset:0x2c00
	v_max_f32_e32 v166, v134, v134
	v_sub_f32_e32 v165, v164, v134
	v_max_f32_e32 v164, v166, v164
	v_sub_f32_e32 v166, v134, v164
	v_mul_f32_e32 v166, 0x3dd53b94, v166
	v_mfma_f32_32x32x16_bf16 v[32:47], v[136:139], v[248:251], v[32:47]
	ds_read_b64_tr_b16 v[248:249], v162 offset:0x3400
	ds_read_b64_tr_b16 v[250:251], v162 offset:0x3c00
	v_exp_f32_e32 v166, v166
	v_cmp_ge_f32_e32 vcc, s69, v165
	s_cmp_eq_u64 vcc, exec
	s_cselect_b64 s[8:9], -1, 0
	v_cndmask_b32_e64 v207, v166, 1.0, s[8:9]
	v_cndmask_b32_e64 v195, v164, v134, s[8:9]
	v_mul_f32_e32 v168, 0xbdd53b94, v195
	v_mov_b32_e32 v187, v168
	s_waitcnt lgkmcnt(0)
; __device__ __forceinline__ void partialSM(f32x16& p0, f32x16& p1, float& m_reg, float& mn, float& alpha) {
;   constexpr float C = ATT_SCALE * 1.4426950408889634f;
;   float pmax = p0[0];
; #pragma unroll
;   for (int r = 1; r < 16; ++r) pmax = fmaxf(pmax, p0[r]);
; #pragma unroll
;   for (int r = 0; r < 16; ++r) pmax = fmaxf(pmax, p1[r]);
;   { auto rr = __builtin_amdgcn_permlane32_swap(__float_as_uint(pmax), __float_as_uint(pmax), false, false);
;     pmax = fmaxf(__uint_as_float(rr[0]), __uint_as_float(rr[1])); }
;   if (__builtin_expect(__all(pmax - m_reg <= ATT_THR / ATT_SCALE), 1)) { mn = m_reg; alpha = 1.f; }
;   else { mn = fmaxf(m_reg, pmax); alpha = __builtin_amdgcn_exp2f((m_reg - mn) * C); m_reg = mn; }
;   const float mnC = -mn * C;
; #pragma unroll
;   for (int r = 0; r < 16; ++r) p0[r] = fmaf(p0[r], C, mnC);
; #pragma unroll
;   for (int r = 0; r < 16; ++r) p1[r] = fmaf(p1[r], C, mnC);
; #pragma unroll
;   for (int r = 0; r < 16; ++r) p0[r] = __builtin_amdgcn_exp2f(p0[r]);
	v_mfma_f32_32x32x16_bf16 v[32:47], v[140:143], v[156:159], v[32:47]
	v_fmamk_f32 v80, v80, 0x3dd53b94, v168
	v_fmamk_f32 v81, v81, 0x3dd53b94, v168
	v_fmamk_f32 v82, v82, 0x3dd53b94, v168
	v_fmamk_f32 v83, v83, 0x3dd53b94, v168
	v_fmamk_f32 v84, v84, 0x3dd53b94, v168
	v_fmamk_f32 v85, v85, 0x3dd53b94, v168
	v_mfma_f32_32x32x16_bf16 v[16:31], v[210:213], v[148:151], v[16:31]
	ds_read_b64_tr_b16 v[148:149], v162 offset:0x600
	ds_read_b64_tr_b16 v[150:151], v162 offset:0xe00
	ds_read_b64_tr_b16 v[156:157], v162 offset:0x1600
	ds_read_b64_tr_b16 v[158:159], v162 offset:0x1e00
	v_fmamk_f32 v86, v86, 0x3dd53b94, v168
	v_fmamk_f32 v87, v87, 0x3dd53b94, v168
	v_fmamk_f32 v88, v88, 0x3dd53b94, v168
	v_fmamk_f32 v89, v89, 0x3dd53b94, v168
	v_fmamk_f32 v90, v90, 0x3dd53b94, v168
	v_fmamk_f32 v91, v91, 0x3dd53b94, v168
	v_mfma_f32_32x32x16_bf16 v[16:31], v[144:147], v[240:243], v[16:31]
	ds_read_b64_tr_b16 v[240:241], v162 offset:0x2600
	ds_read_b64_tr_b16 v[242:243], v162 offset:0x2e00
	v_fmamk_f32 v92, v92, 0x3dd53b94, v168
	v_fmamk_f32 v93, v93, 0x3dd53b94, v168
	v_fmamk_f32 v94, v94, 0x3dd53b94, v168
	v_fmac_f32_e32 v187, 0x3dd53b94, v95
	v_fmamk_f32 v134, v72, 0x3dd53b94, v168
	v_fmamk_f32 v135, v73, 0x3dd53b94, v168
	v_mfma_f32_32x32x16_bf16 v[16:31], v[136:139], v[244:247], v[16:31]
	ds_read_b64_tr_b16 v[244:245], v162 offset:0x3600
	ds_read_b64_tr_b16 v[246:247], v162 offset:0x3e00
	v_exp_f32_e32 v217, v81
	v_exp_f32_e32 v218, v82
	v_exp_f32_e32 v220, v83
	v_exp_f32_e32 v221, v84
	s_waitcnt lgkmcnt(0)
	v_mfma_f32_32x32x16_bf16 v[16:31], v[140:143], v[248:251], v[16:31]
	v_exp_f32_e32 v223, v85
	v_exp_f32_e32 v222, v86
	v_exp_f32_e32 v224, v87
	v_exp_f32_e32 v209, v88
	v_mfma_f32_32x32x16_bf16 v[0:15], v[210:213], v[148:151], v[0:15]
	v_fmamk_f32 v148, v74, 0x3dd53b94, v168
	v_fmamk_f32 v149, v75, 0x3dd53b94, v168
	v_exp_f32_e32 v214, v91
	v_exp_f32_e32 v215, v93
	v_exp_f32_e32 v216, v94
	v_mfma_f32_32x32x16_bf16 v[0:15], v[144:147], v[156:159], v[0:15]
	v_fmamk_f32 v146, v64, 0x3dd53b94, v168
	v_fmamk_f32 v147, v65, 0x3dd53b94, v168
	v_fmamk_f32 v144, v66, 0x3dd53b94, v168
	v_fmamk_f32 v145, v67, 0x3dd53b94, v168
	v_exp_f32_e32 v219, v187
	v_exp_f32_e32 v213, v80
	v_mfma_f32_32x32x16_bf16 v[0:15], v[136:139], v[240:243], v[0:15]
	v_fmamk_f32 v136, v70, 0x3dd53b94, v168
	v_fmamk_f32 v137, v71, 0x3dd53b94, v168
	v_fmamk_f32 v138, v78, 0x3dd53b94, v168
	v_fmamk_f32 v139, v79, 0x3dd53b94, v168
	v_exp_f32_e32 v210, v89
	v_exp_f32_e32 v211, v90
	v_mfma_f32_32x32x16_bf16 v[0:15], v[140:143], v[244:247], v[0:15]
	v_fmamk_f32 v140, v68, 0x3dd53b94, v168
	v_fmamk_f32 v141, v69, 0x3dd53b94, v168
	v_fmamk_f32 v142, v76, 0x3dd53b94, v168
	v_fmamk_f32 v143, v77, 0x3dd53b94, v168
	v_exp_f32_e32 v212, v92
	v_cmp_gt_f32_e32 vcc, 1.0, v207
	s_cbranch_vccz .LBB0_361
	s_and_saveexec_b64 s[10:11], s[6:7]
	ds_write_b32 v160, v207 offset:128
	s_or_b64 exec, exec, s[10:11]
	s_waitcnt lgkmcnt(0)
	v_add_u32_e32 v150, v253, v128
	ds_read_b128 v[240:243], v150 offset:224
	ds_read_b128 v[244:247], v150 offset:192
	ds_read_b128 v[248:251], v150 offset:160
	ds_read_b128 v[156:159], v150 offset:128
	s_waitcnt lgkmcnt(3)
	v_pk_mul_f32 v[60:61], v[60:61], v[240:241]
	s_waitcnt lgkmcnt(2)
	v_pk_mul_f32 v[56:57], v[56:57], v[244:245]
	s_waitcnt lgkmcnt(1)
	v_pk_mul_f32 v[52:53], v[52:53], v[248:249]
	v_pk_mul_f32 v[62:63], v[62:63], v[242:243]
	v_pk_mul_f32 v[58:59], v[58:59], v[246:247]
	v_pk_mul_f32 v[54:55], v[54:55], v[250:251]
	s_waitcnt lgkmcnt(0)
	v_pk_mul_f32 v[50:51], v[50:51], v[158:159]
	v_pk_mul_f32 v[48:49], v[48:49], v[156:157]
	v_pk_mul_f32 v[44:45], v[44:45], v[240:241]
	v_pk_mul_f32 v[40:41], v[40:41], v[244:245]
	v_pk_mul_f32 v[36:37], v[36:37], v[248:249]
	v_pk_mul_f32 v[46:47], v[46:47], v[242:243]
	v_pk_mul_f32 v[42:43], v[42:43], v[246:247]
	v_pk_mul_f32 v[38:39], v[38:39], v[250:251]
	v_pk_mul_f32 v[34:35], v[34:35], v[158:159]
	v_pk_mul_f32 v[32:33], v[32:33], v[156:157]
	v_pk_mul_f32 v[28:29], v[28:29], v[240:241]
	v_pk_mul_f32 v[24:25], v[24:25], v[244:245]
	v_pk_mul_f32 v[20:21], v[20:21], v[248:249]
	v_pk_mul_f32 v[30:31], v[30:31], v[242:243]
	v_pk_mul_f32 v[26:27], v[26:27], v[246:247]
	v_pk_mul_f32 v[22:23], v[22:23], v[250:251]
	v_pk_mul_f32 v[18:19], v[18:19], v[158:159]
	v_pk_mul_f32 v[16:17], v[16:17], v[156:157]
	v_pk_mul_f32 v[12:13], v[12:13], v[240:241]
	v_pk_mul_f32 v[8:9], v[8:9], v[244:245]
	v_pk_mul_f32 v[4:5], v[4:5], v[248:249]
	v_pk_mul_f32 v[14:15], v[14:15], v[242:243]
	v_pk_mul_f32 v[10:11], v[10:11], v[246:247]
	v_pk_mul_f32 v[6:7], v[6:7], v[250:251]
	v_pk_mul_f32 v[2:3], v[2:3], v[158:159]
	v_pk_mul_f32 v[0:1], v[0:1], v[156:157]
.LBB0_361:
	v_add_f32_e32 v64, v205, v206
	v_fmac_f32_e32 v64, v188, v161
	v_add_f32_e32 v161, v225, v226
	s_add_i32 s78, s78, 2
	v_fmac_f32_e32 v161, v64, v208
	s_cmp_ge_u32 s78, s77
	s_waitcnt vmcnt(0)
	s_waitcnt lgkmcnt(0)
	s_barrier
	s_cbranch_scc1 .LBB0_363
	v_mov_b32_e32 v188, v207
	s_branch .LBB0_353
